# v8 + nt (streaming) hint on the 16 gate loads of the branch epilogue so the merged RMW tile stays in L2
# baseline (speedup 1.0000x reference)
; __device__ __forceinline__ unsigned pk2(float lo, float hi) { f32x2_t v = {lo, hi}; bf16x2_t b = __builtin_convertvector(v, bf16x2_t); return __builtin_bit_cast(unsigned, b); }
; __device__ __forceinline__ float bflo(unsigned w) { return __uint_as_float(w << 16); }
; __device__ __forceinline__ float bfhi(unsigned w) { return __uint_as_float(w & 0xffff0000u); }
;     __device__ __forceinline__ void operator()(const f32x4 (&acc)[2][2][4][2], const Unit& us, int wr, int wc, int fr, int fq) const {
;         const int br = us.pm >> 6; Unit u; u.pm = us.pm & 63; u.pn = us.pn & 3;
;         const int row0 = u.pm * 256 + wr * 64 + fr;
; #pragma unroll
;         for (int ai = 0; ai < 2; ++ai)
; #pragma unroll
;             for (int m = 0; m < 4; ++m) {
;                 const int row = row0 + ai * 128 + m * 16;
; #pragma unroll
;                 for (int bj = 0; bj < 2; ++bj) {
;                     const int col = u.pn * 256 + bj * 128 + wc * 32 + 8 * fq;
;                     const u32x4 g = *(const u32x4*)(gates + (unsigned)(row * NG + br * DM + col));
;                     const f32x4 v0 = acc[ai][bj][m][0], v1 = acc[ai][bj][m][1];
;                     float o[8];
;                     o[0] = bflo(g.x) * v0[0]; o[1] = bfhi(g.x) * v0[1]; o[2] = bflo(g.y) * v0[2]; o[3] = bfhi(g.y) * v0[3];
;                     o[4] = bflo(g.z) * v1[0]; o[5] = bfhi(g.z) * v1[1]; o[6] = bflo(g.w) * v1[2]; o[7] = bfhi(g.w) * v1[3];
;                     bf16_t* dst = merged + (unsigned)(row * DM + col);
;                     if (br > 0) {
;                         const u32x4 p = *(const u32x4*)dst;
;                         o[0] += bflo(p.x); o[1] += bfhi(p.x); o[2] += bflo(p.y); o[3] += bfhi(p.y);
;                         o[4] += bflo(p.z); o[5] += bfhi(p.z); o[6] += bflo(p.w); o[7] += bfhi(p.w);
;                     }
;                     u32x4 w; w.x = pk2(o[0], o[1]); w.y = pk2(o[2], o[3]); w.z = pk2(o[4], o[5]); w.w = pk2(o[6], o[7]);
;                     *(u32x4*)dst = w;
;                 }
;                 asm volatile("" ::: "memory");
;             }
.LBB0_350:
	s_lshl_b32 s3, s44, 8
	s_and_b32 s3, s3, 0x3f00
	v_add_u32_e32 v145, s3, v213
	s_lshl_b32 s3, s42, 8
	s_ashr_i32 s2, s44, 6
	s_and_b32 s3, s3, 0x300
	v_or_b32_e32 v144, s3, v143
	v_mul_lo_u32 v64, v145, s76
	v_lshlrev_b32_e32 v237, 10, v145
	v_lshl_add_u32 v64, s2, 10, v64
	v_add_lshl_u32 v237, v237, v144, 1
	v_add_lshl_u32 v64, v64, v144, 1
	v_mov_b64_e32 v[234:235], v[204:205]
	v_mov_b32_e32 v236, v212
	v_mov_b32_e32 v250, v237
	v_mov_b64_e32 v[204:205], 0xff
	v_mov_b32_e32 v212, 1
	v_mov_b32_e32 v242, 0x358637bd
	s_cmp_lt_i32 s2, 1
	global_load_dwordx4 v[154:157], v64, s[36:37] nt
	global_load_dwordx4 v[158:161], v64, s[36:37] offset:256 nt
	v_add_u32_e32 v64, 0x18000, v64
	global_load_dwordx4 v[162:165], v64, s[36:37] nt
	global_load_dwordx4 v[166:169], v64, s[36:37] offset:256 nt
	v_add_u32_e32 v64, 0x18000, v64
	global_load_dwordx4 v[170:173], v64, s[36:37] nt
	global_load_dwordx4 v[174:177], v64, s[36:37] offset:256 nt
	v_add_u32_e32 v64, 0x18000, v64
	global_load_dwordx4 v[178:181], v64, s[36:37] nt
	global_load_dwordx4 v[182:185], v64, s[36:37] offset:256 nt
	v_add_u32_e32 v64, 0x78000, v64
	global_load_dwordx4 v[186:189], v64, s[36:37] nt
	global_load_dwordx4 v[190:193], v64, s[36:37] offset:256 nt
	v_add_u32_e32 v64, 0x18000, v64
	global_load_dwordx4 v[194:197], v64, s[36:37] nt
	global_load_dwordx4 v[198:201], v64, s[36:37] offset:256 nt
	v_add_u32_e32 v64, 0x18000, v64
	global_load_dwordx4 v[206:209], v64, s[36:37] nt
	global_load_dwordx4 v[214:217], v64, s[36:37] offset:256 nt
	v_add_u32_e32 v64, 0x18000, v64
	global_load_dwordx4 v[218:221], v64, s[36:37] nt
	global_load_dwordx4 v[222:225], v64, s[36:37] offset:256 nt
	s_cbranch_scc1 .Lbr_ep_first
	global_load_dwordx4 v[226:229], v250, s[6:7]
	global_load_dwordx4 v[230:233], v250, s[6:7] offset:256
	v_add_u32_e32 v250, 0x8000, v250
	global_load_dwordx4 v[238:241], v250, s[6:7]
	global_load_dwordx4 v[246:249], v250, s[6:7] offset:256
	v_add_u32_e32 v250, 0x8000, v250
	global_load_dwordx4 v[144:147], v250, s[6:7]
	global_load_dwordx4 v[148:151], v250, s[6:7] offset:256
	v_add_u32_e32 v250, 0x8000, v250
	s_waitcnt vmcnt(5)
	v_lshlrev_b32_e32 v138, 16, v154
	v_and_b32_e32 v139, 0xffff0000, v154
	v_lshlrev_b32_e32 v152, 16, v155
	v_and_b32_e32 v153, 0xffff0000, v155
	v_lshlrev_b32_e32 v210, 16, v156
	v_and_b32_e32 v211, 0xffff0000, v156
	v_lshlrev_b32_e32 v202, 16, v157
	v_and_b32_e32 v203, 0xffff0000, v157
	v_pk_mul_f32 v[126:127], v[126:127], v[138:139]
	v_pk_mul_f32 v[128:129], v[128:129], v[152:153]
	v_pk_mul_f32 v[122:123], v[122:123], v[210:211]
	v_pk_mul_f32 v[124:125], v[124:125], v[202:203]
	v_lshlrev_b32_e32 v138, 16, v226
	v_and_b32_e32 v139, 0xffff0000, v226
	v_lshlrev_b32_e32 v152, 16, v227
	v_and_b32_e32 v153, 0xffff0000, v227
	v_lshlrev_b32_e32 v210, 16, v228
	v_and_b32_e32 v211, 0xffff0000, v228
	v_lshlrev_b32_e32 v202, 16, v229
	v_and_b32_e32 v203, 0xffff0000, v229
	v_pk_add_f32 v[126:127], v[126:127], v[138:139]
	v_pk_add_f32 v[128:129], v[128:129], v[152:153]
	v_pk_add_f32 v[122:123], v[122:123], v[210:211]
	v_pk_add_f32 v[124:125], v[124:125], v[202:203]
	v_cvt_pk_bf16_f32 v126, v126, v127
	v_cvt_pk_bf16_f32 v127, v128, v129
	v_cvt_pk_bf16_f32 v128, v122, v123
	v_cvt_pk_bf16_f32 v129, v124, v125
	global_store_dwordx4 v237, v[126:129], s[6:7]
	global_load_dwordx4 v[226:229], v250, s[6:7]
	s_waitcnt vmcnt(6)
	v_lshlrev_b32_e32 v138, 16, v158
	v_and_b32_e32 v139, 0xffff0000, v158
	v_lshlrev_b32_e32 v152, 16, v159
	v_and_b32_e32 v153, 0xffff0000, v159
	v_lshlrev_b32_e32 v210, 16, v160
	v_and_b32_e32 v211, 0xffff0000, v160
	v_lshlrev_b32_e32 v202, 16, v161
	v_and_b32_e32 v203, 0xffff0000, v161
	v_pk_mul_f32 v[114:115], v[114:115], v[138:139]
	v_pk_mul_f32 v[116:117], v[116:117], v[152:153]
	v_pk_mul_f32 v[118:119], v[118:119], v[210:211]
	v_pk_mul_f32 v[120:121], v[120:121], v[202:203]
	v_lshlrev_b32_e32 v138, 16, v230
	v_and_b32_e32 v139, 0xffff0000, v230
	v_lshlrev_b32_e32 v152, 16, v231
	v_and_b32_e32 v153, 0xffff0000, v231
	v_lshlrev_b32_e32 v210, 16, v232
	v_and_b32_e32 v211, 0xffff0000, v232
	v_lshlrev_b32_e32 v202, 16, v233
	v_and_b32_e32 v203, 0xffff0000, v233
	v_pk_add_f32 v[114:115], v[114:115], v[138:139]
	v_pk_add_f32 v[116:117], v[116:117], v[152:153]
	v_pk_add_f32 v[118:119], v[118:119], v[210:211]
	v_pk_add_f32 v[120:121], v[120:121], v[202:203]
	v_cvt_pk_bf16_f32 v114, v114, v115
	v_cvt_pk_bf16_f32 v115, v116, v117
	v_cvt_pk_bf16_f32 v116, v118, v119
	v_cvt_pk_bf16_f32 v117, v120, v121
	global_store_dwordx4 v237, v[114:117], s[6:7] offset:256
	v_add_u32_e32 v237, 0x8000, v237
	global_load_dwordx4 v[230:233], v250, s[6:7] offset:256
	v_add_u32_e32 v250, 0x28000, v250
	s_waitcnt vmcnt(7)
	v_lshlrev_b32_e32 v138, 16, v162
	v_and_b32_e32 v139, 0xffff0000, v162
	v_lshlrev_b32_e32 v152, 16, v163
	v_and_b32_e32 v153, 0xffff0000, v163
	v_lshlrev_b32_e32 v210, 16, v164
	v_and_b32_e32 v211, 0xffff0000, v164
	v_lshlrev_b32_e32 v202, 16, v165
	v_and_b32_e32 v203, 0xffff0000, v165
	v_pk_mul_f32 v[110:111], v[110:111], v[138:139]
	v_pk_mul_f32 v[112:113], v[112:113], v[152:153]
	v_pk_mul_f32 v[106:107], v[106:107], v[210:211]
	v_pk_mul_f32 v[108:109], v[108:109], v[202:203]
	v_lshlrev_b32_e32 v138, 16, v238
	v_and_b32_e32 v139, 0xffff0000, v238
	v_lshlrev_b32_e32 v152, 16, v239
	v_and_b32_e32 v153, 0xffff0000, v239
	v_lshlrev_b32_e32 v210, 16, v240
	v_and_b32_e32 v211, 0xffff0000, v240
	v_lshlrev_b32_e32 v202, 16, v241
	v_and_b32_e32 v203, 0xffff0000, v241
	v_pk_add_f32 v[110:111], v[110:111], v[138:139]
	v_pk_add_f32 v[112:113], v[112:113], v[152:153]
	v_pk_add_f32 v[106:107], v[106:107], v[210:211]
	v_pk_add_f32 v[108:109], v[108:109], v[202:203]
	v_cvt_pk_bf16_f32 v110, v110, v111
	v_cvt_pk_bf16_f32 v111, v112, v113
	v_cvt_pk_bf16_f32 v112, v106, v107
	v_cvt_pk_bf16_f32 v113, v108, v109
	global_store_dwordx4 v237, v[110:113], s[6:7]
	global_load_dwordx4 v[238:241], v250, s[6:7]
	s_waitcnt vmcnt(8)
; __device__ __forceinline__ unsigned pk2(float lo, float hi) { f32x2_t v = {lo, hi}; bf16x2_t b = __builtin_convertvector(v, bf16x2_t); return __builtin_bit_cast(unsigned, b); }
; __device__ __forceinline__ float bflo(unsigned w) { return __uint_as_float(w << 16); }
; __device__ __forceinline__ float bfhi(unsigned w) { return __uint_as_float(w & 0xffff0000u); }
;     __device__ __forceinline__ void operator()(const f32x4 (&acc)[2][2][4][2], const Unit& us, int wr, int wc, int fr, int fq) const {
;     ...
;                 for (int bj = 0; bj < 2; ++bj) {
;                     const int col = u.pn * 256 + bj * 128 + wc * 32 + 8 * fq;
;                     const u32x4 g = *(const u32x4*)(gates + (unsigned)(row * NG + br * DM + col));
;                     const f32x4 v0 = acc[ai][bj][m][0], v1 = acc[ai][bj][m][1];
;                     float o[8];
;                     o[0] = bflo(g.x) * v0[0]; o[1] = bfhi(g.x) * v0[1]; o[2] = bflo(g.y) * v0[2]; o[3] = bfhi(g.y) * v0[3];
;                     o[4] = bflo(g.z) * v1[0]; o[5] = bfhi(g.z) * v1[1]; o[6] = bflo(g.w) * v1[2]; o[7] = bfhi(g.w) * v1[3];
;                     bf16_t* dst = merged + (unsigned)(row * DM + col);
;                     if (br > 0) {
;                         const u32x4 p = *(const u32x4*)dst;
;                         o[0] += bflo(p.x); o[1] += bfhi(p.x); o[2] += bflo(p.y); o[3] += bfhi(p.y);
;                         o[4] += bflo(p.z); o[5] += bfhi(p.z); o[6] += bflo(p.w); o[7] += bfhi(p.w);
;                     }
;                     u32x4 w; w.x = pk2(o[0], o[1]); w.y = pk2(o[2], o[3]); w.z = pk2(o[4], o[5]); w.w = pk2(o[6], o[7]);
;                     *(u32x4*)dst = w;
;                 }
	v_lshlrev_b32_e32 v138, 16, v166
	v_and_b32_e32 v139, 0xffff0000, v166
	v_lshlrev_b32_e32 v152, 16, v167
	v_and_b32_e32 v153, 0xffff0000, v167
	v_lshlrev_b32_e32 v210, 16, v168
	v_and_b32_e32 v211, 0xffff0000, v168
	v_lshlrev_b32_e32 v202, 16, v169
	v_and_b32_e32 v203, 0xffff0000, v169
	v_pk_mul_f32 v[98:99], v[98:99], v[138:139]
	v_pk_mul_f32 v[100:101], v[100:101], v[152:153]
	v_pk_mul_f32 v[102:103], v[102:103], v[210:211]
	v_pk_mul_f32 v[104:105], v[104:105], v[202:203]
	v_lshlrev_b32_e32 v138, 16, v246
	v_and_b32_e32 v139, 0xffff0000, v246
	v_lshlrev_b32_e32 v152, 16, v247
	v_and_b32_e32 v153, 0xffff0000, v247
	v_lshlrev_b32_e32 v210, 16, v248
	v_and_b32_e32 v211, 0xffff0000, v248
	v_lshlrev_b32_e32 v202, 16, v249
	v_and_b32_e32 v203, 0xffff0000, v249
	v_pk_add_f32 v[98:99], v[98:99], v[138:139]
	v_pk_add_f32 v[100:101], v[100:101], v[152:153]
	v_pk_add_f32 v[102:103], v[102:103], v[210:211]
	v_pk_add_f32 v[104:105], v[104:105], v[202:203]
	v_cvt_pk_bf16_f32 v98, v98, v99
	v_cvt_pk_bf16_f32 v99, v100, v101
	v_cvt_pk_bf16_f32 v100, v102, v103
	v_cvt_pk_bf16_f32 v101, v104, v105
	global_store_dwordx4 v237, v[98:101], s[6:7] offset:256
	v_add_u32_e32 v237, 0x8000, v237
	global_load_dwordx4 v[246:249], v250, s[6:7] offset:256
	v_add_u32_e32 v250, 0x8000, v250
	s_waitcnt vmcnt(9)
	v_lshlrev_b32_e32 v138, 16, v170
	v_and_b32_e32 v139, 0xffff0000, v170
	v_lshlrev_b32_e32 v152, 16, v171
	v_and_b32_e32 v153, 0xffff0000, v171
	v_lshlrev_b32_e32 v210, 16, v172
	v_and_b32_e32 v211, 0xffff0000, v172
	v_lshlrev_b32_e32 v202, 16, v173
	v_and_b32_e32 v203, 0xffff0000, v173
	v_pk_mul_f32 v[94:95], v[94:95], v[138:139]
	v_pk_mul_f32 v[96:97], v[96:97], v[152:153]
	v_pk_mul_f32 v[90:91], v[90:91], v[210:211]
	v_pk_mul_f32 v[92:93], v[92:93], v[202:203]
	v_lshlrev_b32_e32 v138, 16, v144
	v_and_b32_e32 v139, 0xffff0000, v144
	v_lshlrev_b32_e32 v152, 16, v145
	v_and_b32_e32 v153, 0xffff0000, v145
	v_lshlrev_b32_e32 v210, 16, v146
	v_and_b32_e32 v211, 0xffff0000, v146
	v_lshlrev_b32_e32 v202, 16, v147
	v_and_b32_e32 v203, 0xffff0000, v147
	v_pk_add_f32 v[94:95], v[94:95], v[138:139]
	v_pk_add_f32 v[96:97], v[96:97], v[152:153]
	v_pk_add_f32 v[90:91], v[90:91], v[210:211]
	v_pk_add_f32 v[92:93], v[92:93], v[202:203]
	v_cvt_pk_bf16_f32 v94, v94, v95
	v_cvt_pk_bf16_f32 v95, v96, v97
	v_cvt_pk_bf16_f32 v96, v90, v91
	v_cvt_pk_bf16_f32 v97, v92, v93
	global_store_dwordx4 v237, v[94:97], s[6:7]
	global_load_dwordx4 v[144:147], v250, s[6:7]
	s_waitcnt vmcnt(10)
	v_lshlrev_b32_e32 v138, 16, v174
	v_and_b32_e32 v139, 0xffff0000, v174
	v_lshlrev_b32_e32 v152, 16, v175
	v_and_b32_e32 v153, 0xffff0000, v175
	v_lshlrev_b32_e32 v210, 16, v176
	v_and_b32_e32 v211, 0xffff0000, v176
	v_lshlrev_b32_e32 v202, 16, v177
	v_and_b32_e32 v203, 0xffff0000, v177
	v_pk_mul_f32 v[82:83], v[82:83], v[138:139]
	v_pk_mul_f32 v[84:85], v[84:85], v[152:153]
	v_pk_mul_f32 v[86:87], v[86:87], v[210:211]
	v_pk_mul_f32 v[88:89], v[88:89], v[202:203]
	v_lshlrev_b32_e32 v138, 16, v148
	v_and_b32_e32 v139, 0xffff0000, v148
	v_lshlrev_b32_e32 v152, 16, v149
	v_and_b32_e32 v153, 0xffff0000, v149
	v_lshlrev_b32_e32 v210, 16, v150
	v_and_b32_e32 v211, 0xffff0000, v150
	v_lshlrev_b32_e32 v202, 16, v151
	v_and_b32_e32 v203, 0xffff0000, v151
	v_pk_add_f32 v[82:83], v[82:83], v[138:139]
	v_pk_add_f32 v[84:85], v[84:85], v[152:153]
	v_pk_add_f32 v[86:87], v[86:87], v[210:211]
	v_pk_add_f32 v[88:89], v[88:89], v[202:203]
	v_cvt_pk_bf16_f32 v82, v82, v83
	v_cvt_pk_bf16_f32 v83, v84, v85
	v_cvt_pk_bf16_f32 v84, v86, v87
	v_cvt_pk_bf16_f32 v85, v88, v89
	global_store_dwordx4 v237, v[82:85], s[6:7] offset:256
	v_add_u32_e32 v237, 0x8000, v237
	global_load_dwordx4 v[148:151], v250, s[6:7] offset:256
	v_add_u32_e32 v250, 0x8000, v250
	s_waitcnt vmcnt(10)
	v_lshlrev_b32_e32 v138, 16, v178
	v_and_b32_e32 v139, 0xffff0000, v178
	v_lshlrev_b32_e32 v152, 16, v179
	v_and_b32_e32 v153, 0xffff0000, v179
	v_lshlrev_b32_e32 v210, 16, v180
	v_and_b32_e32 v211, 0xffff0000, v180
	v_lshlrev_b32_e32 v202, 16, v181
	v_and_b32_e32 v203, 0xffff0000, v181
	v_pk_mul_f32 v[78:79], v[78:79], v[138:139]
	v_pk_mul_f32 v[80:81], v[80:81], v[152:153]
	v_pk_mul_f32 v[74:75], v[74:75], v[210:211]
	v_pk_mul_f32 v[76:77], v[76:77], v[202:203]
	v_lshlrev_b32_e32 v138, 16, v226
	v_and_b32_e32 v139, 0xffff0000, v226
	v_lshlrev_b32_e32 v152, 16, v227
	v_and_b32_e32 v153, 0xffff0000, v227
	v_lshlrev_b32_e32 v210, 16, v228
	v_and_b32_e32 v211, 0xffff0000, v228
	v_lshlrev_b32_e32 v202, 16, v229
	v_and_b32_e32 v203, 0xffff0000, v229
	v_pk_add_f32 v[78:79], v[78:79], v[138:139]
	v_pk_add_f32 v[80:81], v[80:81], v[152:153]
	v_pk_add_f32 v[74:75], v[74:75], v[210:211]
	v_pk_add_f32 v[76:77], v[76:77], v[202:203]
	v_cvt_pk_bf16_f32 v78, v78, v79
	v_cvt_pk_bf16_f32 v79, v80, v81
	v_cvt_pk_bf16_f32 v80, v74, v75
	v_cvt_pk_bf16_f32 v81, v76, v77
	global_store_dwordx4 v237, v[78:81], s[6:7]
	global_load_dwordx4 v[226:229], v250, s[6:7]
	s_waitcnt vmcnt(10)
	v_lshlrev_b32_e32 v138, 16, v182
	v_and_b32_e32 v139, 0xffff0000, v182
	v_lshlrev_b32_e32 v152, 16, v183
	v_and_b32_e32 v153, 0xffff0000, v183
	v_lshlrev_b32_e32 v210, 16, v184
	v_and_b32_e32 v211, 0xffff0000, v184
	v_lshlrev_b32_e32 v202, 16, v185
	v_and_b32_e32 v203, 0xffff0000, v185
	v_pk_mul_f32 v[66:67], v[66:67], v[138:139]
	v_pk_mul_f32 v[68:69], v[68:69], v[152:153]
	v_pk_mul_f32 v[70:71], v[70:71], v[210:211]
	v_pk_mul_f32 v[72:73], v[72:73], v[202:203]
	v_lshlrev_b32_e32 v138, 16, v230
	v_and_b32_e32 v139, 0xffff0000, v230
	v_lshlrev_b32_e32 v152, 16, v231
	v_and_b32_e32 v153, 0xffff0000, v231
	v_lshlrev_b32_e32 v210, 16, v232
	v_and_b32_e32 v211, 0xffff0000, v232
	v_lshlrev_b32_e32 v202, 16, v233
	v_and_b32_e32 v203, 0xffff0000, v233
	v_pk_add_f32 v[66:67], v[66:67], v[138:139]
	v_pk_add_f32 v[68:69], v[68:69], v[152:153]
	v_pk_add_f32 v[70:71], v[70:71], v[210:211]
	v_pk_add_f32 v[72:73], v[72:73], v[202:203]
	v_cvt_pk_bf16_f32 v66, v66, v67
	v_cvt_pk_bf16_f32 v67, v68, v69
	v_cvt_pk_bf16_f32 v68, v70, v71
	v_cvt_pk_bf16_f32 v69, v72, v73
	global_store_dwordx4 v237, v[66:69], s[6:7] offset:256
	v_add_u32_e32 v237, 0x28000, v237
	global_load_dwordx4 v[230:233], v250, s[6:7] offset:256
	v_add_u32_e32 v250, 0x8000, v250
	s_waitcnt vmcnt(10)
; __device__ __forceinline__ unsigned pk2(float lo, float hi) { f32x2_t v = {lo, hi}; bf16x2_t b = __builtin_convertvector(v, bf16x2_t); return __builtin_bit_cast(unsigned, b); }
; __device__ __forceinline__ float bflo(unsigned w) { return __uint_as_float(w << 16); }
; __device__ __forceinline__ float bfhi(unsigned w) { return __uint_as_float(w & 0xffff0000u); }
;     __device__ __forceinline__ void operator()(const f32x4 (&acc)[2][2][4][2], const Unit& us, int wr, int wc, int fr, int fq) const {
;     ...
;                 for (int bj = 0; bj < 2; ++bj) {
;                     const int col = u.pn * 256 + bj * 128 + wc * 32 + 8 * fq;
;                     const u32x4 g = *(const u32x4*)(gates + (unsigned)(row * NG + br * DM + col));
;                     const f32x4 v0 = acc[ai][bj][m][0], v1 = acc[ai][bj][m][1];
;                     float o[8];
;                     o[0] = bflo(g.x) * v0[0]; o[1] = bfhi(g.x) * v0[1]; o[2] = bflo(g.y) * v0[2]; o[3] = bfhi(g.y) * v0[3];
;                     o[4] = bflo(g.z) * v1[0]; o[5] = bfhi(g.z) * v1[1]; o[6] = bflo(g.w) * v1[2]; o[7] = bfhi(g.w) * v1[3];
;                     bf16_t* dst = merged + (unsigned)(row * DM + col);
;                     if (br > 0) {
;                         const u32x4 p = *(const u32x4*)dst;
;                         o[0] += bflo(p.x); o[1] += bfhi(p.x); o[2] += bflo(p.y); o[3] += bfhi(p.y);
;                         o[4] += bflo(p.z); o[5] += bfhi(p.z); o[6] += bflo(p.w); o[7] += bfhi(p.w);
;                     }
;                     u32x4 w; w.x = pk2(o[0], o[1]); w.y = pk2(o[2], o[3]); w.z = pk2(o[4], o[5]); w.w = pk2(o[6], o[7]);
;                     *(u32x4*)dst = w;
;                 }
	v_lshlrev_b32_e32 v138, 16, v186
	v_and_b32_e32 v139, 0xffff0000, v186
	v_lshlrev_b32_e32 v152, 16, v187
	v_and_b32_e32 v153, 0xffff0000, v187
	v_lshlrev_b32_e32 v210, 16, v188
	v_and_b32_e32 v211, 0xffff0000, v188
	v_lshlrev_b32_e32 v202, 16, v189
	v_and_b32_e32 v203, 0xffff0000, v189
	v_pk_mul_f32 v[60:61], v[60:61], v[138:139]
	v_pk_mul_f32 v[62:63], v[62:63], v[152:153]
	v_pk_mul_f32 v[56:57], v[56:57], v[210:211]
	v_pk_mul_f32 v[58:59], v[58:59], v[202:203]
	v_lshlrev_b32_e32 v138, 16, v238
	v_and_b32_e32 v139, 0xffff0000, v238
	v_lshlrev_b32_e32 v152, 16, v239
	v_and_b32_e32 v153, 0xffff0000, v239
	v_lshlrev_b32_e32 v210, 16, v240
	v_and_b32_e32 v211, 0xffff0000, v240
	v_lshlrev_b32_e32 v202, 16, v241
	v_and_b32_e32 v203, 0xffff0000, v241
	v_pk_add_f32 v[60:61], v[60:61], v[138:139]
	v_pk_add_f32 v[62:63], v[62:63], v[152:153]
	v_pk_add_f32 v[56:57], v[56:57], v[210:211]
	v_pk_add_f32 v[58:59], v[58:59], v[202:203]
	v_cvt_pk_bf16_f32 v60, v60, v61
	v_cvt_pk_bf16_f32 v61, v62, v63
	v_cvt_pk_bf16_f32 v62, v56, v57
	v_cvt_pk_bf16_f32 v63, v58, v59
	global_store_dwordx4 v237, v[60:63], s[6:7]
	global_load_dwordx4 v[238:241], v250, s[6:7]
	s_waitcnt vmcnt(10)
	v_lshlrev_b32_e32 v138, 16, v190
	v_and_b32_e32 v139, 0xffff0000, v190
	v_lshlrev_b32_e32 v152, 16, v191
	v_and_b32_e32 v153, 0xffff0000, v191
	v_lshlrev_b32_e32 v210, 16, v192
	v_and_b32_e32 v211, 0xffff0000, v192
	v_lshlrev_b32_e32 v202, 16, v193
	v_and_b32_e32 v203, 0xffff0000, v193
	v_pk_mul_f32 v[48:49], v[48:49], v[138:139]
	v_pk_mul_f32 v[50:51], v[50:51], v[152:153]
	v_pk_mul_f32 v[52:53], v[52:53], v[210:211]
	v_pk_mul_f32 v[54:55], v[54:55], v[202:203]
	v_lshlrev_b32_e32 v138, 16, v246
	v_and_b32_e32 v139, 0xffff0000, v246
	v_lshlrev_b32_e32 v152, 16, v247
	v_and_b32_e32 v153, 0xffff0000, v247
	v_lshlrev_b32_e32 v210, 16, v248
	v_and_b32_e32 v211, 0xffff0000, v248
	v_lshlrev_b32_e32 v202, 16, v249
	v_and_b32_e32 v203, 0xffff0000, v249
	v_pk_add_f32 v[48:49], v[48:49], v[138:139]
	v_pk_add_f32 v[50:51], v[50:51], v[152:153]
	v_pk_add_f32 v[52:53], v[52:53], v[210:211]
	v_pk_add_f32 v[54:55], v[54:55], v[202:203]
	v_cvt_pk_bf16_f32 v48, v48, v49
	v_cvt_pk_bf16_f32 v49, v50, v51
	v_cvt_pk_bf16_f32 v50, v52, v53
	v_cvt_pk_bf16_f32 v51, v54, v55
	global_store_dwordx4 v237, v[48:51], s[6:7] offset:256
	v_add_u32_e32 v237, 0x8000, v237
	global_load_dwordx4 v[246:249], v250, s[6:7] offset:256
	s_waitcnt vmcnt(10)
	v_lshlrev_b32_e32 v138, 16, v194
	v_and_b32_e32 v139, 0xffff0000, v194
	v_lshlrev_b32_e32 v152, 16, v195
	v_and_b32_e32 v153, 0xffff0000, v195
	v_lshlrev_b32_e32 v210, 16, v196
	v_and_b32_e32 v211, 0xffff0000, v196
	v_lshlrev_b32_e32 v202, 16, v197
	v_and_b32_e32 v203, 0xffff0000, v197
	v_pk_mul_f32 v[44:45], v[44:45], v[138:139]
	v_pk_mul_f32 v[46:47], v[46:47], v[152:153]
	v_pk_mul_f32 v[40:41], v[40:41], v[210:211]
	v_pk_mul_f32 v[42:43], v[42:43], v[202:203]
	v_lshlrev_b32_e32 v138, 16, v144
	v_and_b32_e32 v139, 0xffff0000, v144
	v_lshlrev_b32_e32 v152, 16, v145
	v_and_b32_e32 v153, 0xffff0000, v145
	v_lshlrev_b32_e32 v210, 16, v146
	v_and_b32_e32 v211, 0xffff0000, v146
	v_lshlrev_b32_e32 v202, 16, v147
	v_and_b32_e32 v203, 0xffff0000, v147
	v_pk_add_f32 v[44:45], v[44:45], v[138:139]
	v_pk_add_f32 v[46:47], v[46:47], v[152:153]
	v_pk_add_f32 v[40:41], v[40:41], v[210:211]
	v_pk_add_f32 v[42:43], v[42:43], v[202:203]
	v_cvt_pk_bf16_f32 v44, v44, v45
	v_cvt_pk_bf16_f32 v45, v46, v47
	v_cvt_pk_bf16_f32 v46, v40, v41
	v_cvt_pk_bf16_f32 v47, v42, v43
	global_store_dwordx4 v237, v[44:47], s[6:7]
	s_waitcnt vmcnt(9)
	v_lshlrev_b32_e32 v138, 16, v198
	v_and_b32_e32 v139, 0xffff0000, v198
	v_lshlrev_b32_e32 v152, 16, v199
	v_and_b32_e32 v153, 0xffff0000, v199
	v_lshlrev_b32_e32 v210, 16, v200
	v_and_b32_e32 v211, 0xffff0000, v200
	v_lshlrev_b32_e32 v202, 16, v201
	v_and_b32_e32 v203, 0xffff0000, v201
	v_pk_mul_f32 v[32:33], v[32:33], v[138:139]
	v_pk_mul_f32 v[34:35], v[34:35], v[152:153]
	v_pk_mul_f32 v[36:37], v[36:37], v[210:211]
	v_pk_mul_f32 v[38:39], v[38:39], v[202:203]
	v_lshlrev_b32_e32 v138, 16, v148
	v_and_b32_e32 v139, 0xffff0000, v148
	v_lshlrev_b32_e32 v152, 16, v149
	v_and_b32_e32 v153, 0xffff0000, v149
	v_lshlrev_b32_e32 v210, 16, v150
	v_and_b32_e32 v211, 0xffff0000, v150
	v_lshlrev_b32_e32 v202, 16, v151
	v_and_b32_e32 v203, 0xffff0000, v151
	v_pk_add_f32 v[32:33], v[32:33], v[138:139]
	v_pk_add_f32 v[34:35], v[34:35], v[152:153]
	v_pk_add_f32 v[36:37], v[36:37], v[210:211]
	v_pk_add_f32 v[38:39], v[38:39], v[202:203]
	v_cvt_pk_bf16_f32 v32, v32, v33
	v_cvt_pk_bf16_f32 v33, v34, v35
	v_cvt_pk_bf16_f32 v34, v36, v37
	v_cvt_pk_bf16_f32 v35, v38, v39
	global_store_dwordx4 v237, v[32:35], s[6:7] offset:256
	v_add_u32_e32 v237, 0x8000, v237
	s_waitcnt vmcnt(8)
; __device__ __forceinline__ unsigned pk2(float lo, float hi) { f32x2_t v = {lo, hi}; bf16x2_t b = __builtin_convertvector(v, bf16x2_t); return __builtin_bit_cast(unsigned, b); }
; __device__ __forceinline__ float bflo(unsigned w) { return __uint_as_float(w << 16); }
; __device__ __forceinline__ float bfhi(unsigned w) { return __uint_as_float(w & 0xffff0000u); }
;     __device__ __forceinline__ void operator()(const f32x4 (&acc)[2][2][4][2], const Unit& us, int wr, int wc, int fr, int fq) const {
;     ...
;                 for (int bj = 0; bj < 2; ++bj) {
;                     const int col = u.pn * 256 + bj * 128 + wc * 32 + 8 * fq;
;                     const u32x4 g = *(const u32x4*)(gates + (unsigned)(row * NG + br * DM + col));
;                     const f32x4 v0 = acc[ai][bj][m][0], v1 = acc[ai][bj][m][1];
;                     float o[8];
;                     o[0] = bflo(g.x) * v0[0]; o[1] = bfhi(g.x) * v0[1]; o[2] = bflo(g.y) * v0[2]; o[3] = bfhi(g.y) * v0[3];
;                     o[4] = bflo(g.z) * v1[0]; o[5] = bfhi(g.z) * v1[1]; o[6] = bflo(g.w) * v1[2]; o[7] = bfhi(g.w) * v1[3];
;                     bf16_t* dst = merged + (unsigned)(row * DM + col);
;                     if (br > 0) {
;                         const u32x4 p = *(const u32x4*)dst;
;                         o[0] += bflo(p.x); o[1] += bfhi(p.x); o[2] += bflo(p.y); o[3] += bfhi(p.y);
;                         o[4] += bflo(p.z); o[5] += bfhi(p.z); o[6] += bflo(p.w); o[7] += bfhi(p.w);
;                     }
;                     u32x4 w; w.x = pk2(o[0], o[1]); w.y = pk2(o[2], o[3]); w.z = pk2(o[4], o[5]); w.w = pk2(o[6], o[7]);
;                     *(u32x4*)dst = w;
;                 }
	v_lshlrev_b32_e32 v138, 16, v206
	v_and_b32_e32 v139, 0xffff0000, v206
	v_lshlrev_b32_e32 v152, 16, v207
	v_and_b32_e32 v153, 0xffff0000, v207
	v_lshlrev_b32_e32 v210, 16, v208
	v_and_b32_e32 v211, 0xffff0000, v208
	v_lshlrev_b32_e32 v202, 16, v209
	v_and_b32_e32 v203, 0xffff0000, v209
	v_pk_mul_f32 v[28:29], v[28:29], v[138:139]
	v_pk_mul_f32 v[30:31], v[30:31], v[152:153]
	v_pk_mul_f32 v[24:25], v[24:25], v[210:211]
	v_pk_mul_f32 v[26:27], v[26:27], v[202:203]
	v_lshlrev_b32_e32 v138, 16, v226
	v_and_b32_e32 v139, 0xffff0000, v226
	v_lshlrev_b32_e32 v152, 16, v227
	v_and_b32_e32 v153, 0xffff0000, v227
	v_lshlrev_b32_e32 v210, 16, v228
	v_and_b32_e32 v211, 0xffff0000, v228
	v_lshlrev_b32_e32 v202, 16, v229
	v_and_b32_e32 v203, 0xffff0000, v229
	v_pk_add_f32 v[28:29], v[28:29], v[138:139]
	v_pk_add_f32 v[30:31], v[30:31], v[152:153]
	v_pk_add_f32 v[24:25], v[24:25], v[210:211]
	v_pk_add_f32 v[26:27], v[26:27], v[202:203]
	v_cvt_pk_bf16_f32 v28, v28, v29
	v_cvt_pk_bf16_f32 v29, v30, v31
	v_cvt_pk_bf16_f32 v30, v24, v25
	v_cvt_pk_bf16_f32 v31, v26, v27
	global_store_dwordx4 v237, v[28:31], s[6:7]
	s_waitcnt vmcnt(7)
	v_lshlrev_b32_e32 v138, 16, v214
	v_and_b32_e32 v139, 0xffff0000, v214
	v_lshlrev_b32_e32 v152, 16, v215
	v_and_b32_e32 v153, 0xffff0000, v215
	v_lshlrev_b32_e32 v210, 16, v216
	v_and_b32_e32 v211, 0xffff0000, v216
	v_lshlrev_b32_e32 v202, 16, v217
	v_and_b32_e32 v203, 0xffff0000, v217
	v_pk_mul_f32 v[16:17], v[16:17], v[138:139]
	v_pk_mul_f32 v[18:19], v[18:19], v[152:153]
	v_pk_mul_f32 v[20:21], v[20:21], v[210:211]
	v_pk_mul_f32 v[22:23], v[22:23], v[202:203]
	v_lshlrev_b32_e32 v138, 16, v230
	v_and_b32_e32 v139, 0xffff0000, v230
	v_lshlrev_b32_e32 v152, 16, v231
	v_and_b32_e32 v153, 0xffff0000, v231
	v_lshlrev_b32_e32 v210, 16, v232
	v_and_b32_e32 v211, 0xffff0000, v232
	v_lshlrev_b32_e32 v202, 16, v233
	v_and_b32_e32 v203, 0xffff0000, v233
	v_pk_add_f32 v[16:17], v[16:17], v[138:139]
	v_pk_add_f32 v[18:19], v[18:19], v[152:153]
	v_pk_add_f32 v[20:21], v[20:21], v[210:211]
	v_pk_add_f32 v[22:23], v[22:23], v[202:203]
	v_cvt_pk_bf16_f32 v16, v16, v17
	v_cvt_pk_bf16_f32 v17, v18, v19
	v_cvt_pk_bf16_f32 v18, v20, v21
	v_cvt_pk_bf16_f32 v19, v22, v23
	global_store_dwordx4 v237, v[16:19], s[6:7] offset:256
	v_add_u32_e32 v237, 0x8000, v237
	s_waitcnt vmcnt(6)
	v_lshlrev_b32_e32 v138, 16, v218
	v_and_b32_e32 v139, 0xffff0000, v218
	v_lshlrev_b32_e32 v152, 16, v219
	v_and_b32_e32 v153, 0xffff0000, v219
	v_lshlrev_b32_e32 v210, 16, v220
	v_and_b32_e32 v211, 0xffff0000, v220
	v_lshlrev_b32_e32 v202, 16, v221
	v_and_b32_e32 v203, 0xffff0000, v221
	v_pk_mul_f32 v[8:9], v[8:9], v[138:139]
	v_pk_mul_f32 v[10:11], v[10:11], v[152:153]
	v_pk_mul_f32 v[12:13], v[12:13], v[210:211]
	v_pk_mul_f32 v[14:15], v[14:15], v[202:203]
	v_lshlrev_b32_e32 v138, 16, v238
	v_and_b32_e32 v139, 0xffff0000, v238
	v_lshlrev_b32_e32 v152, 16, v239
	v_and_b32_e32 v153, 0xffff0000, v239
	v_lshlrev_b32_e32 v210, 16, v240
	v_and_b32_e32 v211, 0xffff0000, v240
	v_lshlrev_b32_e32 v202, 16, v241
	v_and_b32_e32 v203, 0xffff0000, v241
	v_pk_add_f32 v[8:9], v[8:9], v[138:139]
	v_pk_add_f32 v[10:11], v[10:11], v[152:153]
	v_pk_add_f32 v[12:13], v[12:13], v[210:211]
	v_pk_add_f32 v[14:15], v[14:15], v[202:203]
	v_cvt_pk_bf16_f32 v8, v8, v9
	v_cvt_pk_bf16_f32 v9, v10, v11
	v_cvt_pk_bf16_f32 v10, v12, v13
	v_cvt_pk_bf16_f32 v11, v14, v15
	global_store_dwordx4 v237, v[8:11], s[6:7]
	s_waitcnt vmcnt(5)
	v_lshlrev_b32_e32 v138, 16, v222
	v_and_b32_e32 v139, 0xffff0000, v222
	v_lshlrev_b32_e32 v152, 16, v223
	v_and_b32_e32 v153, 0xffff0000, v223
	v_lshlrev_b32_e32 v210, 16, v224
	v_and_b32_e32 v211, 0xffff0000, v224
	v_lshlrev_b32_e32 v202, 16, v225
	v_and_b32_e32 v203, 0xffff0000, v225
	v_pk_mul_f32 v[0:1], v[0:1], v[138:139]
	v_pk_mul_f32 v[2:3], v[2:3], v[152:153]
	v_pk_mul_f32 v[4:5], v[4:5], v[210:211]
	v_pk_mul_f32 v[6:7], v[6:7], v[202:203]
	v_lshlrev_b32_e32 v138, 16, v246
	v_and_b32_e32 v139, 0xffff0000, v246
	v_lshlrev_b32_e32 v152, 16, v247
	v_and_b32_e32 v153, 0xffff0000, v247
	v_lshlrev_b32_e32 v210, 16, v248
	v_and_b32_e32 v211, 0xffff0000, v248
	v_lshlrev_b32_e32 v202, 16, v249
	v_and_b32_e32 v203, 0xffff0000, v249
	v_pk_add_f32 v[0:1], v[0:1], v[138:139]
	v_pk_add_f32 v[2:3], v[2:3], v[152:153]
	v_pk_add_f32 v[4:5], v[4:5], v[210:211]
	v_pk_add_f32 v[6:7], v[6:7], v[202:203]
	v_cvt_pk_bf16_f32 v0, v0, v1
	v_cvt_pk_bf16_f32 v1, v2, v3
	v_cvt_pk_bf16_f32 v2, v4, v5
	v_cvt_pk_bf16_f32 v3, v6, v7
	global_store_dwordx4 v237, v[0:3], s[6:7] offset:256
	s_branch .Lbr_ep_done
